# GEMM2: first 4 of 16 gate quads of each unit requested at K-loop entry into v240-255 (moves 25% of the epilogue load burst under the K-loop)
# speedup vs baseline: 1.0099x; 1.0099x over previous
.LBB0_739:
	s_ashr_i32 s25, s24, 31
	s_and_b32 s59, s58, 1
	s_lshl_b64 s[26:27], s[24:25], 20
	s_add_u32 s23, s50, s26
	s_addc_u32 s25, s51, s27
	s_lshl_b32 s38, s59, 11
	s_add_u32 s26, s23, s38
	s_addc_u32 s27, s25, 0
	s_and_b64 s[28:29], s[4:5], exec
	s_cselect_b32 s25, s27, s35
	s_cselect_b32 s31, s26, s34
	s_ashr_i32 s23, s22, 31
	s_lshl_b64 s[28:29], s[22:23], 20
	s_add_u32 s23, s70, s28
	s_addc_u32 s29, s71, s29
	s_add_u32 s28, s23, s38
	s_addc_u32 s29, s29, 0
	s_and_b64 s[38:39], s[4:5], exec
	s_cselect_b32 s23, s29, s37
	s_cselect_b32 s65, s28, s36
	s_add_u32 s34, s34, 0x80080
	s_addc_u32 s35, s35, 0
	s_add_u32 s66, s36, 0x100
	s_addc_u32 s67, s37, 0
	s_mov_b32 s68, -2
	v_readlane_b32 s74, v236, 36
	v_readlane_b32 s75, v236, 37
	v_readlane_b32 s76, v236, 0
	v_readlane_b32 s77, v236, 1
	s_cmp_eq_u32 s7, 0
	s_cselect_b32 s75, s75, s77
	s_cselect_b32 s74, s74, s76
	s_lshl_b32 s76, s6, 4
	s_lshl_b32 s77, s30, 1
	s_add_i32 s76, s76, s77
	s_lshl_b32 s76, s76, 16
	s_add_u32 s74, s74, s76
	s_addc_u32 s75, s75, 0
	s_add_u32 s76, s74, 0x10000
	s_addc_u32 s77, s75, 0
	s_add_u32 s78, s74, 0x2000
	s_addc_u32 s79, s75, 0
	s_add_u32 s80, s74, 0x12000
	s_addc_u32 s81, s75, 0
	global_load_dwordx4 v[240:243], v176, s[74:75]
	global_load_dwordx4 v[244:247], v176, s[76:77]
	global_load_dwordx4 v[248:251], v176, s[78:79]
	global_load_dwordx4 v[252:255], v176, s[80:81]

.LBB0_743:
	v_readlane_b32 s72, v236, 22
	v_readlane_b32 s80, v236, 30
	v_readlane_b32 s81, v236, 31
	v_readlane_b32 s82, v236, 32
	v_readlane_b32 s83, v236, 33
	v_readlane_b32 s84, v236, 34
	v_readlane_b32 s85, v236, 35
	s_cmp_lg_u32 s7, 0
	v_readlane_b32 s86, v236, 36
	v_readlane_b32 s87, v236, 37
	s_mov_b64 s[80:81], s[84:85]
	v_readlane_b32 s36, v236, 0
	s_cselect_b64 s[34:35], -1, 0
	s_cmp_eq_u32 s7, 0
	s_mov_b64 s[82:83], s[86:87]
	v_readlane_b32 s37, v236, 1
	s_cselect_b32 s37, s83, s37
	s_cselect_b32 s36, s82, s36
	s_lshl_b32 s7, s6, 4
	s_lshl_b32 s23, s30, 1
	v_lshl_add_u64 v[128:129], s[36:37], 0, v[176:177]
	s_add_i32 s36, s7, s23
	s_ashr_i32 s37, s36, 31
	s_lshl_b64 s[38:39], s[36:37], 16
	s_or_b32 s36, s36, 1
	s_ashr_i32 s37, s36, 31
	v_lshl_add_u64 v[190:191], v[128:129], 0, s[38:39]
	s_lshl_b64 s[36:37], s[36:37], 16
	v_lshl_add_u64 v[192:193], v[128:129], 0, s[36:37]
	v_add_co_u32_e32 v128, vcc, s44, v190


	v_addc_co_u32_e32 v129, vcc, 0, v191, vcc
	v_add_co_u32_e32 v130, vcc, s44, v192
	v_lshl_add_u32 v188, s6, 8, v204
	s_nop 0
	v_addc_co_u32_e32 v131, vcc, 0, v193, vcc


	v_add_co_u32_e32 v128, vcc, s45, v190
	v_ashrrev_i32_e32 v189, 31, v188
	s_nop 0
	v_addc_co_u32_e32 v129, vcc, 0, v191, vcc
	v_add_co_u32_e32 v130, vcc, s45, v192
	v_lshlrev_b64 v[160:161], 12, v[188:189]
	s_nop 0
	v_addc_co_u32_e32 v131, vcc, 0, v193, vcc
	global_load_dwordx4 v[140:143], v[128:129], off
	global_load_dwordx4 v[136:139], v[130:131], off
	v_add_co_u32_e32 v128, vcc, s46, v190
	v_readlane_b32 s74, v236, 24
	s_nop 0
	v_addc_co_u32_e32 v129, vcc, 0, v191, vcc
	v_add_co_u32_e32 v130, vcc, s46, v192
	v_readlane_b32 s75, v236, 25
	s_nop 0
	v_addc_co_u32_e32 v131, vcc, 0, v193, vcc
	global_load_dwordx4 v[132:135], v[128:129], off
	s_nop 0
	global_load_dwordx4 v[128:131], v[130:131], off
	v_readlane_b32 s78, v236, 28
	v_readlane_b32 s79, v236, 29
	v_lshl_or_b32 v186, s30, 8, v206
	v_lshl_add_u64 v[194:195], s[52:53], 0, v[160:161]
	s_mov_b64 s[74:75], s[78:79]
	v_ashrrev_i32_e32 v187, 31, v186
	s_and_b64 vcc, exec, s[34:35]
	v_readlane_b32 s73, v236, 23
	v_readlane_b32 s76, v236, 26
	v_readlane_b32 s77, v236, 27
	s_waitcnt vmcnt(0)
	v_mov_b64_e32 v[156:157], v[240:241]
	v_mov_b64_e32 v[158:159], v[242:243]
	v_mov_b64_e32 v[152:153], v[244:245]
	v_mov_b64_e32 v[154:155], v[246:247]
	v_mov_b64_e32 v[148:149], v[248:249]
	v_mov_b64_e32 v[150:151], v[250:251]
	v_mov_b64_e32 v[144:145], v[252:253]
	v_mov_b64_e32 v[146:147], v[254:255]
	v_lshlrev_b32_e32 v160, 16, v156
	v_and_b32_e32 v161, 0xffff0000, v156
	v_lshlrev_b32_e32 v162, 16, v158
	v_and_b32_e32 v163, 0xffff0000, v158
	v_lshlrev_b32_e32 v208, 16, v157
	v_and_b32_e32 v209, 0xffff0000, v157
	v_lshlrev_b32_e32 v158, 16, v159
	v_and_b32_e32 v159, 0xffff0000, v159
	v_pk_mul_f32 v[160:161], v[124:125], v[160:161]
	v_pk_mul_f32 v[156:157], v[120:121], v[162:163]
	v_pk_mul_f32 v[162:163], v[126:127], v[208:209]
	v_pk_mul_f32 v[158:159], v[122:123], v[158:159]
	s_cbranch_vccz .LBB0_745
	v_cvt_pk_bf16_f32 v160, v160, v161
	v_cvt_pk_bf16_f32 v161, v162, v163
	v_cvt_pk_bf16_f32 v162, v156, v157
	v_cvt_pk_bf16_f32 v163, v158, v159
	v_lshl_add_u64 v[156:157], v[186:187], 1, v[194:195]
	global_store_dwordx4 v[156:157], v[160:163], off
	s_branch .LBB0_746
